# P0 x->XB + row sum of squares hand-written: all 4 rows of a wave loaded up front (32 loads in flight)
# baseline (speedup 1.0000x reference)
; __device__ __forceinline__ unsigned cvt_pk_bf16(float lo, float hi) { unsigned r; asm volatile("v_cvt_pk_bf16_f32 %0, %1, %2" : "=v"(r) : "v"(lo), "v"(hi)); return r; }
;     ...
;     const float* x = a.in[0]; bf16_t* XB = (bf16_t*)(ws + WS_XB); float* SSQ = (float*)(ws + WS_PART);
;     for (int row = gw; row < pg8::MROWS; row += NGW) {
;         const f32x4* xr = (const f32x4*)(x + (size_t)row * 2048) + lane; u32x2* xo = (u32x2*)(XB + (size_t)row * 2048) + lane; float ss = 0.f;
; #pragma unroll
;         for (int j = 0; j < 8; ++j) { const f32x4 v = xr[64 * j]; ss += (v[0] * v[0] + v[1] * v[1]) + (v[2] * v[2] + v[3] * v[3]); u32x2 o; o.x = cvt_pk_bf16(v[0], v[1]); o.y = cvt_pk_bf16(v[2], v[3]); xo[64 * j] = o; }
;         ss = wave_sum(ss); if (lane < 8) SSQ[(size_t)lane * pg8::MROWS + row] = lane == 0 ? ss : 0.f;
;     }
.LBB0_53:
	s_cmpk_lt_i32 s12, 0x2000
	v_and_b32_e32 v8, 63, v204
	s_cbranch_scc0 .LBB0_58
	s_cmpk_lg_u32 s3, 0x100
	s_cbranch_scc1 .Lxp_orig
	v_readlane_b32 s16, v250, 2
	v_readlane_b32 s17, v250, 3
	s_add_u32 s20, s92, 0xe200000
	s_addc_u32 s21, s93, 0
	s_add_u32 s36, s92, 0x1fa00000
	s_addc_u32 s37, s93, 0
	v_cmp_gt_u32_e32 vcc, 8, v8
	v_cmp_eq_u32_e64 s[4:5], 0, v8
	s_add_u32 s18, s16, 0x1000
	s_addc_u32 s19, s17, 0
	s_add_i32 s38, s12, 0
	s_lshl_b32 s38, s38, 13
	v_lshl_add_u32 v9, v8, 4, s38
	global_load_dwordx4 v[18:21], v9, s[16:17] offset:0
	global_load_dwordx4 v[22:25], v9, s[16:17] offset:1024
	global_load_dwordx4 v[26:29], v9, s[16:17] offset:2048
	global_load_dwordx4 v[30:33], v9, s[16:17] offset:3072
	global_load_dwordx4 v[34:37], v9, s[18:19] offset:0
	global_load_dwordx4 v[38:41], v9, s[18:19] offset:1024
	global_load_dwordx4 v[42:45], v9, s[18:19] offset:2048
	global_load_dwordx4 v[46:49], v9, s[18:19] offset:3072
	s_add_i32 s38, s12, 2048
	s_lshl_b32 s38, s38, 13
	v_lshl_add_u32 v9, v8, 4, s38
	global_load_dwordx4 v[50:53], v9, s[16:17] offset:0
	global_load_dwordx4 v[54:57], v9, s[16:17] offset:1024
	global_load_dwordx4 v[58:61], v9, s[16:17] offset:2048
	global_load_dwordx4 v[62:65], v9, s[16:17] offset:3072
	global_load_dwordx4 v[66:69], v9, s[18:19] offset:0
	global_load_dwordx4 v[70:73], v9, s[18:19] offset:1024
	global_load_dwordx4 v[74:77], v9, s[18:19] offset:2048
	global_load_dwordx4 v[78:81], v9, s[18:19] offset:3072
	s_add_i32 s38, s12, 4096
	s_lshl_b32 s38, s38, 13
	v_lshl_add_u32 v9, v8, 4, s38
	global_load_dwordx4 v[82:85], v9, s[16:17] offset:0
	global_load_dwordx4 v[86:89], v9, s[16:17] offset:1024
	global_load_dwordx4 v[90:93], v9, s[16:17] offset:2048
	global_load_dwordx4 v[94:97], v9, s[16:17] offset:3072
	global_load_dwordx4 v[98:101], v9, s[18:19] offset:0
	global_load_dwordx4 v[102:105], v9, s[18:19] offset:1024
	global_load_dwordx4 v[106:109], v9, s[18:19] offset:2048
	global_load_dwordx4 v[110:113], v9, s[18:19] offset:3072
	s_add_i32 s38, s12, 6144
	s_lshl_b32 s38, s38, 13
	v_lshl_add_u32 v9, v8, 4, s38
	global_load_dwordx4 v[114:117], v9, s[16:17] offset:0
	global_load_dwordx4 v[118:121], v9, s[16:17] offset:1024
	global_load_dwordx4 v[122:125], v9, s[16:17] offset:2048
	global_load_dwordx4 v[126:129], v9, s[16:17] offset:3072
	global_load_dwordx4 v[130:133], v9, s[18:19] offset:0
	global_load_dwordx4 v[134:137], v9, s[18:19] offset:1024
	global_load_dwordx4 v[138:141], v9, s[18:19] offset:2048
	global_load_dwordx4 v[142:145], v9, s[18:19] offset:3072
	s_add_i32 s38, s12, 0
	s_lshl_b32 s39, s38, 12
	v_lshl_add_u32 v10, v8, 3, s39
	s_lshl_b32 s39, s38, 2
	v_lshl_add_u32 v11, v8, 15, s39
	s_waitcnt vmcnt(24)
	v_cvt_pk_bf16_f32 v146, v18, v19
	v_cvt_pk_bf16_f32 v147, v20, v21
	global_store_dwordx2 v10, v[146:147], s[20:21] offset:0
	v_cvt_pk_bf16_f32 v148, v22, v23
	v_cvt_pk_bf16_f32 v149, v24, v25
	global_store_dwordx2 v10, v[148:149], s[20:21] offset:512
	v_cvt_pk_bf16_f32 v150, v26, v27
	v_cvt_pk_bf16_f32 v151, v28, v29
	global_store_dwordx2 v10, v[150:151], s[20:21] offset:1024
	v_cvt_pk_bf16_f32 v152, v30, v31
	v_cvt_pk_bf16_f32 v153, v32, v33
	global_store_dwordx2 v10, v[152:153], s[20:21] offset:1536
	v_cvt_pk_bf16_f32 v154, v34, v35
	v_cvt_pk_bf16_f32 v155, v36, v37
	global_store_dwordx2 v10, v[154:155], s[20:21] offset:2048
	v_cvt_pk_bf16_f32 v156, v38, v39
	v_cvt_pk_bf16_f32 v157, v40, v41
	global_store_dwordx2 v10, v[156:157], s[20:21] offset:2560
	v_cvt_pk_bf16_f32 v158, v42, v43
	v_cvt_pk_bf16_f32 v159, v44, v45
	global_store_dwordx2 v10, v[158:159], s[20:21] offset:3072
	v_cvt_pk_bf16_f32 v160, v46, v47
	v_cvt_pk_bf16_f32 v161, v48, v49
	global_store_dwordx2 v10, v[160:161], s[20:21] offset:3584
	v_mul_f32_e32 v13, v19, v19
	v_mul_f32_e32 v14, v21, v21
	v_fmac_f32_e32 v13, v18, v18
	v_fmac_f32_e32 v14, v20, v20
	v_add_f32_e32 v12, v13, v14
	v_mul_f32_e32 v13, v23, v23
	v_mul_f32_e32 v14, v25, v25
	v_fmac_f32_e32 v13, v22, v22
	v_fmac_f32_e32 v14, v24, v24
	v_add_f32_e32 v13, v13, v14
	v_add_f32_e32 v12, v12, v13
	v_mul_f32_e32 v13, v27, v27
	v_mul_f32_e32 v14, v29, v29
	v_fmac_f32_e32 v13, v26, v26
	v_fmac_f32_e32 v14, v28, v28
	v_add_f32_e32 v13, v13, v14
	v_add_f32_e32 v12, v12, v13
	v_mul_f32_e32 v13, v31, v31
	v_mul_f32_e32 v14, v33, v33
	v_fmac_f32_e32 v13, v30, v30
	v_fmac_f32_e32 v14, v32, v32
	v_add_f32_e32 v13, v13, v14
	v_add_f32_e32 v12, v12, v13
	v_mul_f32_e32 v13, v35, v35
	v_mul_f32_e32 v14, v37, v37
	v_fmac_f32_e32 v13, v34, v34
	v_fmac_f32_e32 v14, v36, v36
	v_add_f32_e32 v13, v13, v14
	v_add_f32_e32 v12, v12, v13
	v_mul_f32_e32 v13, v39, v39
	v_mul_f32_e32 v14, v41, v41
	v_fmac_f32_e32 v13, v38, v38
	v_fmac_f32_e32 v14, v40, v40
	v_add_f32_e32 v13, v13, v14
	v_add_f32_e32 v12, v12, v13
	v_mul_f32_e32 v13, v43, v43
	v_mul_f32_e32 v14, v45, v45
	v_fmac_f32_e32 v13, v42, v42
	v_fmac_f32_e32 v14, v44, v44
	v_add_f32_e32 v13, v13, v14
	v_add_f32_e32 v12, v12, v13
	v_mul_f32_e32 v13, v47, v47
	v_mul_f32_e32 v14, v49, v49
	v_fmac_f32_e32 v13, v46, v46
	v_fmac_f32_e32 v14, v48, v48
	v_add_f32_e32 v13, v13, v14
	v_add_f32_e32 v12, v12, v13
	s_nop 1
	v_mov_b32_dpp v13, v12 quad_perm:[1,0,3,2] row_mask:0xf bank_mask:0xf
	v_add_f32_e32 v12, v12, v13
	s_nop 1
	v_mov_b32_dpp v13, v12 quad_perm:[2,3,0,1] row_mask:0xf bank_mask:0xf
	v_add_f32_e32 v12, v12, v13
	s_nop 1
	v_mov_b32_dpp v13, v12 row_half_mirror row_mask:0xf bank_mask:0xf
	v_add_f32_e32 v12, v12, v13
	s_nop 1
	v_mov_b32_dpp v13, v12 row_mirror row_mask:0xf bank_mask:0xf
	v_add_f32_e32 v12, v12, v13
	v_mov_b32_e32 v13, v12
	s_nop 1
	v_permlane16_swap_b32_e32 v12, v13
	v_add_f32_e32 v12, v12, v13
	v_mov_b32_e32 v13, v12
	s_nop 1
	v_permlane32_swap_b32_e32 v12, v13
	v_add_f32_e32 v12, v12, v13
	v_cndmask_b32_e64 v12, 0, v12, s[4:5]
	s_and_saveexec_b64 s[6:7], vcc
	global_store_dword v11, v12, s[36:37]
	s_or_b64 exec, exec, s[6:7]
	s_add_i32 s38, s12, 2048
	s_lshl_b32 s39, s38, 12
	v_lshl_add_u32 v10, v8, 3, s39
	s_lshl_b32 s39, s38, 2
	v_lshl_add_u32 v11, v8, 15, s39
	s_waitcnt vmcnt(25)
; __device__ __forceinline__ unsigned cvt_pk_bf16(float lo, float hi) { unsigned r; asm volatile("v_cvt_pk_bf16_f32 %0, %1, %2" : "=v"(r) : "v"(lo), "v"(hi)); return r; }
;     ...
;     for (int row = gw; row < pg8::MROWS; row += NGW) {
;         const f32x4* xr = (const f32x4*)(x + (size_t)row * 2048) + lane; u32x2* xo = (u32x2*)(XB + (size_t)row * 2048) + lane; float ss = 0.f;
; #pragma unroll
;         for (int j = 0; j < 8; ++j) { const f32x4 v = xr[64 * j]; ss += (v[0] * v[0] + v[1] * v[1]) + (v[2] * v[2] + v[3] * v[3]); u32x2 o; o.x = cvt_pk_bf16(v[0], v[1]); o.y = cvt_pk_bf16(v[2], v[3]); xo[64 * j] = o; }
;         ss = wave_sum(ss); if (lane < 8) SSQ[(size_t)lane * pg8::MROWS + row] = lane == 0 ? ss : 0.f;
;     }
	v_cvt_pk_bf16_f32 v146, v50, v51
	v_cvt_pk_bf16_f32 v147, v52, v53
	global_store_dwordx2 v10, v[146:147], s[20:21] offset:0
	v_cvt_pk_bf16_f32 v148, v54, v55
	v_cvt_pk_bf16_f32 v149, v56, v57
	global_store_dwordx2 v10, v[148:149], s[20:21] offset:512
	v_cvt_pk_bf16_f32 v150, v58, v59
	v_cvt_pk_bf16_f32 v151, v60, v61
	global_store_dwordx2 v10, v[150:151], s[20:21] offset:1024
	v_cvt_pk_bf16_f32 v152, v62, v63
	v_cvt_pk_bf16_f32 v153, v64, v65
	global_store_dwordx2 v10, v[152:153], s[20:21] offset:1536
	v_cvt_pk_bf16_f32 v154, v66, v67
	v_cvt_pk_bf16_f32 v155, v68, v69
	global_store_dwordx2 v10, v[154:155], s[20:21] offset:2048
	v_cvt_pk_bf16_f32 v156, v70, v71
	v_cvt_pk_bf16_f32 v157, v72, v73
	global_store_dwordx2 v10, v[156:157], s[20:21] offset:2560
	v_cvt_pk_bf16_f32 v158, v74, v75
	v_cvt_pk_bf16_f32 v159, v76, v77
	global_store_dwordx2 v10, v[158:159], s[20:21] offset:3072
	v_cvt_pk_bf16_f32 v160, v78, v79
	v_cvt_pk_bf16_f32 v161, v80, v81
	global_store_dwordx2 v10, v[160:161], s[20:21] offset:3584
	v_mul_f32_e32 v13, v51, v51
	v_mul_f32_e32 v14, v53, v53
	v_fmac_f32_e32 v13, v50, v50
	v_fmac_f32_e32 v14, v52, v52
	v_add_f32_e32 v12, v13, v14
	v_mul_f32_e32 v13, v55, v55
	v_mul_f32_e32 v14, v57, v57
	v_fmac_f32_e32 v13, v54, v54
	v_fmac_f32_e32 v14, v56, v56
	v_add_f32_e32 v13, v13, v14
	v_add_f32_e32 v12, v12, v13
	v_mul_f32_e32 v13, v59, v59
	v_mul_f32_e32 v14, v61, v61
	v_fmac_f32_e32 v13, v58, v58
	v_fmac_f32_e32 v14, v60, v60
	v_add_f32_e32 v13, v13, v14
	v_add_f32_e32 v12, v12, v13
	v_mul_f32_e32 v13, v63, v63
	v_mul_f32_e32 v14, v65, v65
	v_fmac_f32_e32 v13, v62, v62
	v_fmac_f32_e32 v14, v64, v64
	v_add_f32_e32 v13, v13, v14
	v_add_f32_e32 v12, v12, v13
	v_mul_f32_e32 v13, v67, v67
	v_mul_f32_e32 v14, v69, v69
	v_fmac_f32_e32 v13, v66, v66
	v_fmac_f32_e32 v14, v68, v68
	v_add_f32_e32 v13, v13, v14
	v_add_f32_e32 v12, v12, v13
	v_mul_f32_e32 v13, v71, v71
	v_mul_f32_e32 v14, v73, v73
	v_fmac_f32_e32 v13, v70, v70
	v_fmac_f32_e32 v14, v72, v72
	v_add_f32_e32 v13, v13, v14
	v_add_f32_e32 v12, v12, v13
	v_mul_f32_e32 v13, v75, v75
	v_mul_f32_e32 v14, v77, v77
	v_fmac_f32_e32 v13, v74, v74
	v_fmac_f32_e32 v14, v76, v76
	v_add_f32_e32 v13, v13, v14
	v_add_f32_e32 v12, v12, v13
	v_mul_f32_e32 v13, v79, v79
	v_mul_f32_e32 v14, v81, v81
	v_fmac_f32_e32 v13, v78, v78
	v_fmac_f32_e32 v14, v80, v80
	v_add_f32_e32 v13, v13, v14
	v_add_f32_e32 v12, v12, v13
	s_nop 1
	v_mov_b32_dpp v13, v12 quad_perm:[1,0,3,2] row_mask:0xf bank_mask:0xf
	v_add_f32_e32 v12, v12, v13
	s_nop 1
	v_mov_b32_dpp v13, v12 quad_perm:[2,3,0,1] row_mask:0xf bank_mask:0xf
	v_add_f32_e32 v12, v12, v13
	s_nop 1
	v_mov_b32_dpp v13, v12 row_half_mirror row_mask:0xf bank_mask:0xf
	v_add_f32_e32 v12, v12, v13
	s_nop 1
	v_mov_b32_dpp v13, v12 row_mirror row_mask:0xf bank_mask:0xf
	v_add_f32_e32 v12, v12, v13
	v_mov_b32_e32 v13, v12
	s_nop 1
	v_permlane16_swap_b32_e32 v12, v13
	v_add_f32_e32 v12, v12, v13
	v_mov_b32_e32 v13, v12
	s_nop 1
	v_permlane32_swap_b32_e32 v12, v13
	v_add_f32_e32 v12, v12, v13
	v_cndmask_b32_e64 v12, 0, v12, s[4:5]
	s_and_saveexec_b64 s[6:7], vcc
	global_store_dword v11, v12, s[36:37]
	s_or_b64 exec, exec, s[6:7]
	s_add_i32 s38, s12, 4096
	s_lshl_b32 s39, s38, 12
	v_lshl_add_u32 v10, v8, 3, s39
	s_lshl_b32 s39, s38, 2
	v_lshl_add_u32 v11, v8, 15, s39
	s_waitcnt vmcnt(26)
	v_cvt_pk_bf16_f32 v146, v82, v83
	v_cvt_pk_bf16_f32 v147, v84, v85
	global_store_dwordx2 v10, v[146:147], s[20:21] offset:0
	v_cvt_pk_bf16_f32 v148, v86, v87
	v_cvt_pk_bf16_f32 v149, v88, v89
	global_store_dwordx2 v10, v[148:149], s[20:21] offset:512
	v_cvt_pk_bf16_f32 v150, v90, v91
	v_cvt_pk_bf16_f32 v151, v92, v93
	global_store_dwordx2 v10, v[150:151], s[20:21] offset:1024
	v_cvt_pk_bf16_f32 v152, v94, v95
	v_cvt_pk_bf16_f32 v153, v96, v97
	global_store_dwordx2 v10, v[152:153], s[20:21] offset:1536
	v_cvt_pk_bf16_f32 v154, v98, v99
	v_cvt_pk_bf16_f32 v155, v100, v101
	global_store_dwordx2 v10, v[154:155], s[20:21] offset:2048
	v_cvt_pk_bf16_f32 v156, v102, v103
	v_cvt_pk_bf16_f32 v157, v104, v105
	global_store_dwordx2 v10, v[156:157], s[20:21] offset:2560
	v_cvt_pk_bf16_f32 v158, v106, v107
	v_cvt_pk_bf16_f32 v159, v108, v109
	global_store_dwordx2 v10, v[158:159], s[20:21] offset:3072
	v_cvt_pk_bf16_f32 v160, v110, v111
	v_cvt_pk_bf16_f32 v161, v112, v113
	global_store_dwordx2 v10, v[160:161], s[20:21] offset:3584
	v_mul_f32_e32 v13, v83, v83
	v_mul_f32_e32 v14, v85, v85
	v_fmac_f32_e32 v13, v82, v82
	v_fmac_f32_e32 v14, v84, v84
	v_add_f32_e32 v12, v13, v14
	v_mul_f32_e32 v13, v87, v87
	v_mul_f32_e32 v14, v89, v89
	v_fmac_f32_e32 v13, v86, v86
	v_fmac_f32_e32 v14, v88, v88
	v_add_f32_e32 v13, v13, v14
	v_add_f32_e32 v12, v12, v13
	v_mul_f32_e32 v13, v91, v91
	v_mul_f32_e32 v14, v93, v93
	v_fmac_f32_e32 v13, v90, v90
	v_fmac_f32_e32 v14, v92, v92
	v_add_f32_e32 v13, v13, v14
	v_add_f32_e32 v12, v12, v13
	v_mul_f32_e32 v13, v95, v95
	v_mul_f32_e32 v14, v97, v97
	v_fmac_f32_e32 v13, v94, v94
	v_fmac_f32_e32 v14, v96, v96
	v_add_f32_e32 v13, v13, v14
	v_add_f32_e32 v12, v12, v13
	v_mul_f32_e32 v13, v99, v99
	v_mul_f32_e32 v14, v101, v101
	v_fmac_f32_e32 v13, v98, v98
	v_fmac_f32_e32 v14, v100, v100
	v_add_f32_e32 v13, v13, v14
	v_add_f32_e32 v12, v12, v13
	v_mul_f32_e32 v13, v103, v103
	v_mul_f32_e32 v14, v105, v105
	v_fmac_f32_e32 v13, v102, v102
	v_fmac_f32_e32 v14, v104, v104
	v_add_f32_e32 v13, v13, v14
	v_add_f32_e32 v12, v12, v13
	v_mul_f32_e32 v13, v107, v107
	v_mul_f32_e32 v14, v109, v109
	v_fmac_f32_e32 v13, v106, v106
	v_fmac_f32_e32 v14, v108, v108
	v_add_f32_e32 v13, v13, v14
	v_add_f32_e32 v12, v12, v13
	v_mul_f32_e32 v13, v111, v111
	v_mul_f32_e32 v14, v113, v113
	v_fmac_f32_e32 v13, v110, v110
	v_fmac_f32_e32 v14, v112, v112
	v_add_f32_e32 v13, v13, v14
	v_add_f32_e32 v12, v12, v13
	s_nop 1
	v_mov_b32_dpp v13, v12 quad_perm:[1,0,3,2] row_mask:0xf bank_mask:0xf
	v_add_f32_e32 v12, v12, v13
	s_nop 1
	v_mov_b32_dpp v13, v12 quad_perm:[2,3,0,1] row_mask:0xf bank_mask:0xf
	v_add_f32_e32 v12, v12, v13
	s_nop 1
	v_mov_b32_dpp v13, v12 row_half_mirror row_mask:0xf bank_mask:0xf
	v_add_f32_e32 v12, v12, v13
	s_nop 1
	v_mov_b32_dpp v13, v12 row_mirror row_mask:0xf bank_mask:0xf
	v_add_f32_e32 v12, v12, v13
	v_mov_b32_e32 v13, v12
	s_nop 1
	v_permlane16_swap_b32_e32 v12, v13
	v_add_f32_e32 v12, v12, v13
	v_mov_b32_e32 v13, v12
	s_nop 1
	v_permlane32_swap_b32_e32 v12, v13
	v_add_f32_e32 v12, v12, v13
	v_cndmask_b32_e64 v12, 0, v12, s[4:5]
	s_and_saveexec_b64 s[6:7], vcc
	global_store_dword v11, v12, s[36:37]
	s_or_b64 exec, exec, s[6:7]
	s_add_i32 s38, s12, 6144
	s_lshl_b32 s39, s38, 12
	v_lshl_add_u32 v10, v8, 3, s39
	s_lshl_b32 s39, s38, 2
	v_lshl_add_u32 v11, v8, 15, s39
	s_waitcnt vmcnt(27)
; __device__ __forceinline__ unsigned cvt_pk_bf16(float lo, float hi) { unsigned r; asm volatile("v_cvt_pk_bf16_f32 %0, %1, %2" : "=v"(r) : "v"(lo), "v"(hi)); return r; }
;     ...
;     for (int row = gw; row < pg8::MROWS; row += NGW) {
;         const f32x4* xr = (const f32x4*)(x + (size_t)row * 2048) + lane; u32x2* xo = (u32x2*)(XB + (size_t)row * 2048) + lane; float ss = 0.f;
; #pragma unroll
;         for (int j = 0; j < 8; ++j) { const f32x4 v = xr[64 * j]; ss += (v[0] * v[0] + v[1] * v[1]) + (v[2] * v[2] + v[3] * v[3]); u32x2 o; o.x = cvt_pk_bf16(v[0], v[1]); o.y = cvt_pk_bf16(v[2], v[3]); xo[64 * j] = o; }
;         ss = wave_sum(ss); if (lane < 8) SSQ[(size_t)lane * pg8::MROWS + row] = lane == 0 ? ss : 0.f;
;     }
	v_cvt_pk_bf16_f32 v146, v114, v115
	v_cvt_pk_bf16_f32 v147, v116, v117
	global_store_dwordx2 v10, v[146:147], s[20:21] offset:0
	v_cvt_pk_bf16_f32 v148, v118, v119
	v_cvt_pk_bf16_f32 v149, v120, v121
	global_store_dwordx2 v10, v[148:149], s[20:21] offset:512
	v_cvt_pk_bf16_f32 v150, v122, v123
	v_cvt_pk_bf16_f32 v151, v124, v125
	global_store_dwordx2 v10, v[150:151], s[20:21] offset:1024
	v_cvt_pk_bf16_f32 v152, v126, v127
	v_cvt_pk_bf16_f32 v153, v128, v129
	global_store_dwordx2 v10, v[152:153], s[20:21] offset:1536
	v_cvt_pk_bf16_f32 v154, v130, v131
	v_cvt_pk_bf16_f32 v155, v132, v133
	global_store_dwordx2 v10, v[154:155], s[20:21] offset:2048
	v_cvt_pk_bf16_f32 v156, v134, v135
	v_cvt_pk_bf16_f32 v157, v136, v137
	global_store_dwordx2 v10, v[156:157], s[20:21] offset:2560
	v_cvt_pk_bf16_f32 v158, v138, v139
	v_cvt_pk_bf16_f32 v159, v140, v141
	global_store_dwordx2 v10, v[158:159], s[20:21] offset:3072
	v_cvt_pk_bf16_f32 v160, v142, v143
	v_cvt_pk_bf16_f32 v161, v144, v145
	global_store_dwordx2 v10, v[160:161], s[20:21] offset:3584
	v_mul_f32_e32 v13, v115, v115
	v_mul_f32_e32 v14, v117, v117
	v_fmac_f32_e32 v13, v114, v114
	v_fmac_f32_e32 v14, v116, v116
	v_add_f32_e32 v12, v13, v14
	v_mul_f32_e32 v13, v119, v119
	v_mul_f32_e32 v14, v121, v121
	v_fmac_f32_e32 v13, v118, v118
	v_fmac_f32_e32 v14, v120, v120
	v_add_f32_e32 v13, v13, v14
	v_add_f32_e32 v12, v12, v13
	v_mul_f32_e32 v13, v123, v123
	v_mul_f32_e32 v14, v125, v125
	v_fmac_f32_e32 v13, v122, v122
	v_fmac_f32_e32 v14, v124, v124
	v_add_f32_e32 v13, v13, v14
	v_add_f32_e32 v12, v12, v13
	v_mul_f32_e32 v13, v127, v127
	v_mul_f32_e32 v14, v129, v129
	v_fmac_f32_e32 v13, v126, v126
	v_fmac_f32_e32 v14, v128, v128
	v_add_f32_e32 v13, v13, v14
	v_add_f32_e32 v12, v12, v13
	v_mul_f32_e32 v13, v131, v131
	v_mul_f32_e32 v14, v133, v133
	v_fmac_f32_e32 v13, v130, v130
	v_fmac_f32_e32 v14, v132, v132
	v_add_f32_e32 v13, v13, v14
	v_add_f32_e32 v12, v12, v13
	v_mul_f32_e32 v13, v135, v135
	v_mul_f32_e32 v14, v137, v137
	v_fmac_f32_e32 v13, v134, v134
	v_fmac_f32_e32 v14, v136, v136
	v_add_f32_e32 v13, v13, v14
	v_add_f32_e32 v12, v12, v13
	v_mul_f32_e32 v13, v139, v139
	v_mul_f32_e32 v14, v141, v141
	v_fmac_f32_e32 v13, v138, v138
	v_fmac_f32_e32 v14, v140, v140
	v_add_f32_e32 v13, v13, v14
	v_add_f32_e32 v12, v12, v13
	v_mul_f32_e32 v13, v143, v143
	v_mul_f32_e32 v14, v145, v145
	v_fmac_f32_e32 v13, v142, v142
	v_fmac_f32_e32 v14, v144, v144
	v_add_f32_e32 v13, v13, v14
	v_add_f32_e32 v12, v12, v13
	s_nop 1
	v_mov_b32_dpp v13, v12 quad_perm:[1,0,3,2] row_mask:0xf bank_mask:0xf
	v_add_f32_e32 v12, v12, v13
	s_nop 1
	v_mov_b32_dpp v13, v12 quad_perm:[2,3,0,1] row_mask:0xf bank_mask:0xf
	v_add_f32_e32 v12, v12, v13
	s_nop 1
	v_mov_b32_dpp v13, v12 row_half_mirror row_mask:0xf bank_mask:0xf
	v_add_f32_e32 v12, v12, v13
	s_nop 1
	v_mov_b32_dpp v13, v12 row_mirror row_mask:0xf bank_mask:0xf
	v_add_f32_e32 v12, v12, v13
	v_mov_b32_e32 v13, v12
	s_nop 1
	v_permlane16_swap_b32_e32 v12, v13
	v_add_f32_e32 v12, v12, v13
	v_mov_b32_e32 v13, v12
	s_nop 1
	v_permlane32_swap_b32_e32 v12, v13
	v_add_f32_e32 v12, v12, v13
	v_cndmask_b32_e64 v12, 0, v12, s[4:5]
	s_and_saveexec_b64 s[6:7], vcc
	global_store_dword v11, v12, s[36:37]
	s_or_b64 exec, exec, s[6:7]
	s_branch .LBB0_58
.Lxp_orig:
	v_lshlrev_b32_e32 v4, 15, v8
	v_mov_b32_e32 v5, 0
	s_ashr_i32 s13, s12, 31
	v_lshl_add_u64 v[2:3], s[12:13], 2, v[4:5]
	s_mov_b64 s[6:7], 0x1fa00000
	s_ashr_i32 s15, s14, 31
	v_lshl_add_u64 v[2:3], v[2:3], 0, s[6:7]
	s_lshl_b64 s[16:17], s[14:15], 2
	s_lshl_b64 s[6:7], s[12:13], 13
	v_readlane_b32 s36, v250, 2
	v_readlane_b32 s37, v250, 3
	s_add_u32 s6, s36, s6
	v_lshlrev_b32_e32 v4, 4, v8
	s_addc_u32 s7, s37, s7
	v_mbcnt_lo_u32_b32 v9, -1, 0
	v_lshl_add_u64 v[4:5], s[6:7], 0, v[4:5]
	s_mov_b64 s[6:7], 0x1000
	v_mbcnt_hi_u32_b32 v9, -1, v9
	v_lshl_add_u64 v[4:5], v[4:5], 0, s[6:7]
	s_lshl_b64 s[6:7], s[12:13], 12
	v_and_b32_e32 v10, 64, v9
	v_cmp_gt_u32_e32 vcc, 8, v8
	v_cmp_eq_u32_e64 s[4:5], 0, v8
	s_lshl_b64 s[18:19], s[14:15], 13
	v_lshl_or_b32 v6, v8, 3, s6
	v_mov_b32_e32 v7, s7
	s_lshl_b64 s[20:21], s[14:15], 12
	s_mov_b32 s13, 0xe200000
	v_add_u32_e32 v10, 64, v10
	v_xor_b32_e32 v11, 1, v9
	v_xor_b32_e32 v12, 2, v9
	v_xor_b32_e32 v13, 4, v9
	v_xor_b32_e32 v14, 8, v9
	v_xor_b32_e32 v15, 16, v9
	v_xor_b32_e32 v16, 32, v9
	s_mov_b32 s15, s12
	v_readlane_b32 s38, v250, 4
	v_readlane_b32 s39, v250, 5
	v_readlane_b32 s40, v250, 6
	v_readlane_b32 s41, v250, 7
	v_readlane_b32 s42, v250, 8
	v_readlane_b32 s43, v250, 9
	v_readlane_b32 s44, v250, 10
	v_readlane_b32 s45, v250, 11
	v_readlane_b32 s46, v250, 12
	v_readlane_b32 s47, v250, 13
	v_readlane_b32 s48, v250, 14
	v_readlane_b32 s49, v250, 15
	v_readlane_b32 s50, v250, 16
	v_readlane_b32 s51, v250, 17
	s_branch .LBB0_56
